# GLA p2 second-direction loops: log-decay MFMA chains + log-sigmoid evaluated 4-wide, software pipelined
# baseline (speedup 1.0000x reference)
.LBB0_680:
	s_add_u32 s62, s71, s60
	s_addc_u32 s63, s74, s61
	s_add_u32 s72, s48, s60
	s_addc_u32 s73, s70, s61
	s_add_u32 s55, s72, s68
	v_lshl_add_u64 v[70:71], s[62:63], 0, v[112:113]
	s_addc_u32 s63, s73, 0
	s_add_u32 s62, s55, 0xafc0800
	v_add_co_u32_e32 v74, vcc, s95, v70
	s_addc_u32 s63, s63, 0
	s_nop 0
	v_addc_co_u32_e32 v75, vcc, 0, v71, vcc
	v_lshl_add_u64 v[86:87], s[62:63], 0, v[114:115]
	v_add_co_u32_e32 v78, vcc, s81, v86
	s_and_b32 s67, s75, 1
	s_nop 0
	v_addc_co_u32_e32 v79, vcc, 0, v87, vcc
	s_cmp_eq_u32 s67, 0
	v_add_co_u32_e32 v82, vcc, s95, v86
	s_cselect_b64 s[64:65], -1, 0
	s_nop 0
	v_addc_co_u32_e32 v83, vcc, 0, v87, vcc
	s_and_b64 s[62:63], s[64:65], exec
	global_load_dwordx4 v[94:97], v[70:71], off
	global_load_dwordx4 v[98:101], v[70:71], off offset:1024
	s_nop 0
	global_load_dwordx4 v[70:73], v[74:75], off
	global_load_dwordx4 v[90:93], v[74:75], off offset:1024
	s_cselect_b32 s55, 0xf0, s69
	global_load_dwordx4 v[74:77], v[86:87], off
	v_add_co_u32_e32 v86, vcc, s96, v86
	v_add3_u32 v105, s55, v177, v175
	s_nop 0
	v_addc_co_u32_e32 v87, vcc, 0, v87, vcc
	global_load_dwordx4 v[78:81], v[78:79], off
	s_nop 0
	global_load_dwordx4 v[82:85], v[82:83], off
	s_nop 0
	global_load_dwordx4 v[86:89], v[86:87], off
	ds_read2_b32 v[140:141], v105 offset1:4
	ds_read2_b32 v[242:243], v105 offset0:8 offset1:12
	s_waitcnt vmcnt(8) lgkmcnt(0)
	v_mfma_f32_16x16x4_f32 v[244:247], v140, v219, 0
	v_mfma_f32_16x16x4_f32 v[244:247], v141, v220, v[244:247]
	v_mfma_f32_16x16x4_f32 v[244:247], v242, v221, v[244:247]
	v_mfma_f32_16x16x4_f32 v[244:247], v243, v222, v[244:247]
	ds_read2_b32 v[140:141], v105 offset0:64 offset1:68
	ds_read2_b32 v[242:243], v105 offset0:72 offset1:76
	s_waitcnt lgkmcnt(0)
	s_nop 9
	v_mfma_f32_16x16x4_f32 v[248:251], v140, v219, 0
	v_mfma_f32_16x16x4_f32 v[248:251], v141, v220, v[248:251]
	v_mfma_f32_16x16x4_f32 v[248:251], v242, v221, v[248:251]
	v_mfma_f32_16x16x4_f32 v[248:251], v243, v222, v[248:251]
	v_add_f32_e32 v241, v223, v244
	v_add_f32_e32 v252, v223, v245
	v_add_f32_e32 v253, v223, v246
	v_add_f32_e32 v254, v223, v247
	v_min_f32_e32 v0, 0, v241
	v_min_f32_e32 v102, 0, v252
	v_min_f32_e32 v103, 0, v253
	v_min_f32_e32 v104, 0, v254
	v_mul_f32_e64 v241, |v241|, s97
	v_mul_f32_e64 v252, |v252|, s97
	v_mul_f32_e64 v253, |v253|, s97
	v_mul_f32_e64 v254, |v254|, s97
	v_exp_f32_e32 v241, v241
	v_exp_f32_e32 v252, v252
	v_exp_f32_e32 v253, v253
	v_exp_f32_e32 v254, v254
	v_add_f32_e32 v241, 1.0, v241
	v_add_f32_e32 v252, 1.0, v252
	v_add_f32_e32 v253, 1.0, v253
	v_add_f32_e32 v254, 1.0, v254
	v_log_f32_e32 v241, v241
	v_log_f32_e32 v252, v252
	v_log_f32_e32 v253, v253
	v_log_f32_e32 v254, v254
	v_fmac_f32_e32 v0, 0xbf317218, v241
	v_fmac_f32_e32 v102, 0xbf317218, v252
	v_fmac_f32_e32 v103, 0xbf317218, v253
	v_fmac_f32_e32 v104, 0xbf317218, v254
	ds_read2_b32 v[140:141], v105 offset0:128 offset1:132
	ds_read2_b32 v[242:243], v105 offset0:136 offset1:140
	s_nop 7
	s_waitcnt lgkmcnt(0)
	v_mfma_f32_16x16x4_f32 v[244:247], v140, v219, 0
	v_mfma_f32_16x16x4_f32 v[244:247], v141, v220, v[244:247]
	v_mfma_f32_16x16x4_f32 v[244:247], v242, v221, v[244:247]
	v_mfma_f32_16x16x4_f32 v[244:247], v243, v222, v[244:247]
	v_add_f32_e32 v241, v223, v248
	v_add_f32_e32 v252, v223, v249
	v_add_f32_e32 v253, v223, v250
	v_add_f32_e32 v254, v223, v251
	v_min_f32_e32 v106, 0, v241
	v_min_f32_e32 v107, 0, v252
	v_min_f32_e32 v108, 0, v253
	v_min_f32_e32 v109, 0, v254
	v_mul_f32_e64 v241, |v241|, s97
	v_mul_f32_e64 v252, |v252|, s97
	v_mul_f32_e64 v253, |v253|, s97
	v_mul_f32_e64 v254, |v254|, s97
	v_exp_f32_e32 v241, v241
	v_exp_f32_e32 v252, v252
	v_exp_f32_e32 v253, v253
	v_exp_f32_e32 v254, v254
	v_add_f32_e32 v241, 1.0, v241
	v_add_f32_e32 v252, 1.0, v252
	v_add_f32_e32 v253, 1.0, v253
	v_add_f32_e32 v254, 1.0, v254
	v_log_f32_e32 v241, v241
	v_log_f32_e32 v252, v252
	v_log_f32_e32 v253, v253
	v_log_f32_e32 v254, v254
	v_fmac_f32_e32 v106, 0xbf317218, v241
	v_fmac_f32_e32 v107, 0xbf317218, v252
	v_fmac_f32_e32 v108, 0xbf317218, v253
	v_fmac_f32_e32 v109, 0xbf317218, v254
	ds_read2_b32 v[140:141], v105 offset0:192 offset1:196
	ds_read2_b32 v[242:243], v105 offset0:200 offset1:204
	s_nop 7
	s_waitcnt lgkmcnt(0)
	v_mfma_f32_16x16x4_f32 v[248:251], v140, v219, 0
	v_mfma_f32_16x16x4_f32 v[248:251], v141, v220, v[248:251]
	v_mfma_f32_16x16x4_f32 v[248:251], v242, v221, v[248:251]
	v_mfma_f32_16x16x4_f32 v[248:251], v243, v222, v[248:251]
	v_add_f32_e32 v241, v223, v244
	v_add_f32_e32 v252, v223, v245
	v_add_f32_e32 v253, v223, v246
	v_add_f32_e32 v254, v223, v247
	v_min_f32_e32 v142, 0, v241
	v_min_f32_e32 v143, 0, v252
	v_min_f32_e32 v144, 0, v253
	v_min_f32_e32 v145, 0, v254
	v_mul_f32_e64 v241, |v241|, s97
	v_mul_f32_e64 v252, |v252|, s97
	v_mul_f32_e64 v253, |v253|, s97
	v_mul_f32_e64 v254, |v254|, s97
	v_exp_f32_e32 v241, v241
	v_exp_f32_e32 v252, v252
	v_exp_f32_e32 v253, v253
	v_exp_f32_e32 v254, v254
	v_add_f32_e32 v241, 1.0, v241
	v_add_f32_e32 v252, 1.0, v252
	v_add_f32_e32 v253, 1.0, v253
	v_add_f32_e32 v254, 1.0, v254
	v_log_f32_e32 v241, v241
	v_log_f32_e32 v252, v252
	v_log_f32_e32 v253, v253
	v_log_f32_e32 v254, v254
	v_fmac_f32_e32 v142, 0xbf317218, v241
	v_fmac_f32_e32 v143, 0xbf317218, v252
	v_fmac_f32_e32 v144, 0xbf317218, v253
	v_fmac_f32_e32 v145, 0xbf317218, v254
	s_nop 9
	v_add_f32_e32 v241, v223, v248
	v_add_f32_e32 v252, v223, v249
	v_add_f32_e32 v253, v223, v250
	v_add_f32_e32 v254, v223, v251
	v_min_f32_e32 v136, 0, v241
	v_min_f32_e32 v137, 0, v252
	v_min_f32_e32 v138, 0, v253
	v_min_f32_e32 v139, 0, v254
	v_mul_f32_e64 v241, |v241|, s97
	v_mul_f32_e64 v252, |v252|, s97
	v_mul_f32_e64 v253, |v253|, s97
	v_mul_f32_e64 v254, |v254|, s97
	v_exp_f32_e32 v241, v241
	v_exp_f32_e32 v252, v252
	v_exp_f32_e32 v253, v253
	v_exp_f32_e32 v254, v254
	v_add_f32_e32 v241, 1.0, v241
	v_add_f32_e32 v252, 1.0, v252
	v_add_f32_e32 v253, 1.0, v253
	v_add_f32_e32 v254, 1.0, v254
	v_log_f32_e32 v241, v241
	v_log_f32_e32 v252, v252
	v_log_f32_e32 v253, v253
	v_log_f32_e32 v254, v254
	v_fmac_f32_e32 v136, 0xbf317218, v241
	v_fmac_f32_e32 v137, 0xbf317218, v252
	v_fmac_f32_e32 v138, 0xbf317218, v253
	v_fmac_f32_e32 v139, 0xbf317218, v254
	v_fma_f32 v105, v139, s0, 0
	v_fmamk_f32 v138, v138, 0x3d800000, v105
	v_fmamk_f32 v137, v137, 0x3d800000, v138
	v_fmamk_f32 v136, v136, 0x3d800000, v137
	v_fmamk_f32 v139, v145, 0x3d800000, v136
	v_fmamk_f32 v140, v144, 0x3d800000, v139
	v_fmamk_f32 v141, v143, 0x3d800000, v140
	v_fmamk_f32 v142, v142, 0x3d800000, v141
	v_fmamk_f32 v109, v109, 0x3d800000, v142
	v_fmamk_f32 v108, v108, 0x3d800000, v109
	v_fmamk_f32 v107, v107, 0x3d800000, v108
	v_fmamk_f32 v106, v106, 0x3d800000, v107
	v_fmamk_f32 v104, v104, 0x3d800000, v106
	v_fmamk_f32 v103, v103, 0x3d800000, v104
	v_fmamk_f32 v102, v102, 0x3d800000, v103
	v_fmamk_f32 v0, v0, 0x3d800000, v102
	ds_bpermute_b32 v144, v188, v0
	ds_bpermute_b32 v145, v189, v0
	ds_bpermute_b32 v143, v187, v0
	s_waitcnt lgkmcnt(2)
	v_cndmask_b32_e64 v144, 0, v144, s[28:29]
	s_waitcnt lgkmcnt(1)
	v_cndmask_b32_e64 v145, v145, 0, s[8:9]
	v_add_f32_e32 v144, v144, v145
	s_waitcnt lgkmcnt(0)
	v_cndmask_b32_e64 v143, 0, v143, s[4:5]
	v_add_f32_e32 v143, v143, v144
	v_add_f32_e32 v0, v143, v0
	v_add_f32_e32 v102, v143, v102
	ds_write2st64_b32 v200, v0, v102 offset0:24 offset1:26
	v_add_f32_e32 v0, v143, v103
	v_add_f32_e32 v102, v143, v104
	ds_write2st64_b32 v200, v0, v102 offset0:28 offset1:30
	v_add_f32_e32 v0, v143, v106
	v_add_f32_e32 v102, v143, v107
	ds_write2st64_b32 v200, v0, v102 offset0:32 offset1:34
	v_add_f32_e32 v0, v143, v108
	v_add_f32_e32 v102, v143, v109
	ds_write2st64_b32 v200, v0, v102 offset0:36 offset1:38
	v_add_f32_e32 v0, v143, v142
	v_add_f32_e32 v102, v143, v141
	ds_write2st64_b32 v200, v0, v102 offset0:40 offset1:42
	v_add_f32_e32 v0, v143, v140
	v_add_f32_e32 v102, v143, v139
	ds_write2st64_b32 v200, v0, v102 offset0:44 offset1:46
	v_add_f32_e32 v0, v143, v136
	v_add_f32_e32 v102, v143, v137
	ds_write2st64_b32 v200, v0, v102 offset0:48 offset1:50
	v_add_f32_e32 v0, v143, v138
	v_add_f32_e32 v102, v143, v105
	ds_write2st64_b32 v200, v0, v102 offset0:52 offset1:54
	s_waitcnt lgkmcnt(0)
	s_barrier
	s_and_saveexec_b64 s[62:63], s[10:11]
	s_cbranch_execz .LBB0_682
	ds_read_b32 v0, v178 offset:6144
	v_lshl_add_u32 v102, s67, 9, v178
	s_waitcnt lgkmcnt(0)
	ds_write_b32 v102, v0 offset:4096

.LBB0_2283:
	s_add_u32 s60, s70, s58
	s_addc_u32 s61, s71, s59
	s_add_u32 s49, s64, s58
	s_addc_u32 s69, s65, s59
	s_add_u32 s53, s49, s0
	v_lshl_add_u64 v[70:71], s[60:61], 0, v[112:113]
	s_addc_u32 s61, s69, 0
	s_add_u32 s60, s53, 0xafc0800
	v_add_co_u32_e32 v74, vcc, s72, v70
	s_addc_u32 s61, s61, 0
	s_nop 0
	v_addc_co_u32_e32 v75, vcc, 0, v71, vcc
	v_lshl_add_u64 v[86:87], s[60:61], 0, v[114:115]
	v_add_co_u32_e32 v78, vcc, s81, v86
	s_and_b32 s68, s74, 1
	s_nop 0
	v_addc_co_u32_e32 v79, vcc, 0, v87, vcc
	s_cmp_eq_u32 s68, 0
	v_add_co_u32_e32 v82, vcc, s72, v86
	s_cselect_b64 s[60:61], -1, 0
	s_nop 0
	v_addc_co_u32_e32 v83, vcc, 0, v87, vcc
	s_and_b64 s[62:63], s[60:61], exec
	global_load_dwordx4 v[94:97], v[70:71], off
	global_load_dwordx4 v[98:101], v[70:71], off offset:1024
	s_nop 0
	global_load_dwordx4 v[70:73], v[74:75], off
	global_load_dwordx4 v[90:93], v[74:75], off offset:1024
	s_cselect_b32 s53, 0xf0, s89
	global_load_dwordx4 v[74:77], v[86:87], off
	v_add_co_u32_e32 v86, vcc, s73, v86
	v_add3_u32 v105, s53, v180, v116
	s_nop 0
	v_addc_co_u32_e32 v87, vcc, 0, v87, vcc
	global_load_dwordx4 v[78:81], v[78:79], off
	s_nop 0
	global_load_dwordx4 v[82:85], v[82:83], off
	s_nop 0
	global_load_dwordx4 v[86:89], v[86:87], off
	ds_read2_b32 v[144:145], v105 offset1:4
	ds_read2_b32 v[242:243], v105 offset0:8 offset1:12
	s_waitcnt vmcnt(8) lgkmcnt(0)
	v_mfma_f32_16x16x4_f32 v[244:247], v144, v223, 0
	v_mfma_f32_16x16x4_f32 v[244:247], v145, v224, v[244:247]
	v_mfma_f32_16x16x4_f32 v[244:247], v242, v225, v[244:247]
	v_mfma_f32_16x16x4_f32 v[244:247], v243, v226, v[244:247]
	ds_read2_b32 v[144:145], v105 offset0:64 offset1:68
	ds_read2_b32 v[242:243], v105 offset0:72 offset1:76
	s_waitcnt lgkmcnt(0)
	s_nop 9
	v_mfma_f32_16x16x4_f32 v[248:251], v144, v223, 0
	v_mfma_f32_16x16x4_f32 v[248:251], v145, v224, v[248:251]
	v_mfma_f32_16x16x4_f32 v[248:251], v242, v225, v[248:251]
	v_mfma_f32_16x16x4_f32 v[248:251], v243, v226, v[248:251]
	v_add_f32_e32 v143, v227, v244
	v_add_f32_e32 v241, v227, v245
	v_add_f32_e32 v252, v227, v246
	v_add_f32_e32 v253, v227, v247
	v_min_f32_e32 v0, 0, v143
	v_min_f32_e32 v102, 0, v241
	v_min_f32_e32 v103, 0, v252
	v_min_f32_e32 v104, 0, v253
	v_mul_f32_e64 v143, |v143|, s66
	v_mul_f32_e64 v241, |v241|, s66
	v_mul_f32_e64 v252, |v252|, s66
	v_mul_f32_e64 v253, |v253|, s66
	v_exp_f32_e32 v143, v143
	v_exp_f32_e32 v241, v241
	v_exp_f32_e32 v252, v252
	v_exp_f32_e32 v253, v253
	v_add_f32_e32 v143, 1.0, v143
	v_add_f32_e32 v241, 1.0, v241
	v_add_f32_e32 v252, 1.0, v252
	v_add_f32_e32 v253, 1.0, v253
	v_log_f32_e32 v143, v143
	v_log_f32_e32 v241, v241
	v_log_f32_e32 v252, v252
	v_log_f32_e32 v253, v253
	v_fmac_f32_e32 v0, 0xbf317218, v143
	v_fmac_f32_e32 v102, 0xbf317218, v241
	v_fmac_f32_e32 v103, 0xbf317218, v252
	v_fmac_f32_e32 v104, 0xbf317218, v253
	ds_read2_b32 v[144:145], v105 offset0:128 offset1:132
	ds_read2_b32 v[242:243], v105 offset0:136 offset1:140
	s_nop 7
	s_waitcnt lgkmcnt(0)
	v_mfma_f32_16x16x4_f32 v[244:247], v144, v223, 0
	v_mfma_f32_16x16x4_f32 v[244:247], v145, v224, v[244:247]
	v_mfma_f32_16x16x4_f32 v[244:247], v242, v225, v[244:247]
	v_mfma_f32_16x16x4_f32 v[244:247], v243, v226, v[244:247]
	v_add_f32_e32 v143, v227, v248
	v_add_f32_e32 v241, v227, v249
	v_add_f32_e32 v252, v227, v250
	v_add_f32_e32 v253, v227, v251
	v_min_f32_e32 v106, 0, v143
	v_min_f32_e32 v107, 0, v241
	v_min_f32_e32 v108, 0, v252
	v_min_f32_e32 v109, 0, v253
	v_mul_f32_e64 v143, |v143|, s66
	v_mul_f32_e64 v241, |v241|, s66
	v_mul_f32_e64 v252, |v252|, s66
	v_mul_f32_e64 v253, |v253|, s66
	v_exp_f32_e32 v143, v143
	v_exp_f32_e32 v241, v241
	v_exp_f32_e32 v252, v252
	v_exp_f32_e32 v253, v253
	v_add_f32_e32 v143, 1.0, v143
	v_add_f32_e32 v241, 1.0, v241
	v_add_f32_e32 v252, 1.0, v252
	v_add_f32_e32 v253, 1.0, v253
	v_log_f32_e32 v143, v143
	v_log_f32_e32 v241, v241
	v_log_f32_e32 v252, v252
	v_log_f32_e32 v253, v253
	v_fmac_f32_e32 v106, 0xbf317218, v143
	v_fmac_f32_e32 v107, 0xbf317218, v241
	v_fmac_f32_e32 v108, 0xbf317218, v252
	v_fmac_f32_e32 v109, 0xbf317218, v253
	ds_read2_b32 v[144:145], v105 offset0:192 offset1:196
	ds_read2_b32 v[242:243], v105 offset0:200 offset1:204
	s_nop 7
	s_waitcnt lgkmcnt(0)
	v_mfma_f32_16x16x4_f32 v[248:251], v144, v223, 0
	v_mfma_f32_16x16x4_f32 v[248:251], v145, v224, v[248:251]
	v_mfma_f32_16x16x4_f32 v[248:251], v242, v225, v[248:251]
	v_mfma_f32_16x16x4_f32 v[248:251], v243, v226, v[248:251]
	v_add_f32_e32 v143, v227, v244
	v_add_f32_e32 v241, v227, v245
	v_add_f32_e32 v252, v227, v246
	v_add_f32_e32 v253, v227, v247
	v_min_f32_e32 v137, 0, v143
	v_min_f32_e32 v146, 0, v241
	v_min_f32_e32 v147, 0, v252
	v_min_f32_e32 v148, 0, v253
	v_mul_f32_e64 v143, |v143|, s66
	v_mul_f32_e64 v241, |v241|, s66
	v_mul_f32_e64 v252, |v252|, s66
	v_mul_f32_e64 v253, |v253|, s66
	v_exp_f32_e32 v143, v143
	v_exp_f32_e32 v241, v241
	v_exp_f32_e32 v252, v252
	v_exp_f32_e32 v253, v253
	v_add_f32_e32 v143, 1.0, v143
	v_add_f32_e32 v241, 1.0, v241
	v_add_f32_e32 v252, 1.0, v252
	v_add_f32_e32 v253, 1.0, v253
	v_log_f32_e32 v143, v143
	v_log_f32_e32 v241, v241
	v_log_f32_e32 v252, v252
	v_log_f32_e32 v253, v253
	v_fmac_f32_e32 v137, 0xbf317218, v143
	v_fmac_f32_e32 v146, 0xbf317218, v241
	v_fmac_f32_e32 v147, 0xbf317218, v252
	v_fmac_f32_e32 v148, 0xbf317218, v253
	s_nop 9
	v_add_f32_e32 v143, v227, v248
	v_add_f32_e32 v241, v227, v249
	v_add_f32_e32 v252, v227, v250
	v_add_f32_e32 v253, v227, v251
	v_min_f32_e32 v135, 0, v143
	v_min_f32_e32 v140, 0, v241
	v_min_f32_e32 v141, 0, v252
	v_min_f32_e32 v142, 0, v253
	v_mul_f32_e64 v143, |v143|, s66
	v_mul_f32_e64 v241, |v241|, s66
	v_mul_f32_e64 v252, |v252|, s66
	v_mul_f32_e64 v253, |v253|, s66
	v_exp_f32_e32 v143, v143
	v_exp_f32_e32 v241, v241
	v_exp_f32_e32 v252, v252
	v_exp_f32_e32 v253, v253
	v_add_f32_e32 v143, 1.0, v143
	v_add_f32_e32 v241, 1.0, v241
	v_add_f32_e32 v252, 1.0, v252
	v_add_f32_e32 v253, 1.0, v253
	v_log_f32_e32 v143, v143
	v_log_f32_e32 v241, v241
	v_log_f32_e32 v252, v252
	v_log_f32_e32 v253, v253
	v_fmac_f32_e32 v135, 0xbf317218, v143
	v_fmac_f32_e32 v140, 0xbf317218, v241
	v_fmac_f32_e32 v141, 0xbf317218, v252
	v_fmac_f32_e32 v142, 0xbf317218, v253
	v_fma_f32 v105, v142, s67, 0
	v_fmamk_f32 v141, v141, 0x3d800000, v105
	v_fmamk_f32 v140, v140, 0x3d800000, v141
	v_fmamk_f32 v135, v135, 0x3d800000, v140
	v_fmamk_f32 v142, v148, 0x3d800000, v135
	v_fmamk_f32 v143, v147, 0x3d800000, v142
	v_fmamk_f32 v144, v146, 0x3d800000, v143
	v_fmamk_f32 v137, v137, 0x3d800000, v144
	v_fmamk_f32 v109, v109, 0x3d800000, v137
	v_fmamk_f32 v108, v108, 0x3d800000, v109
	v_fmamk_f32 v107, v107, 0x3d800000, v108
	v_fmamk_f32 v106, v106, 0x3d800000, v107
	v_fmamk_f32 v104, v104, 0x3d800000, v106
	v_fmamk_f32 v103, v103, 0x3d800000, v104
	v_fmamk_f32 v102, v102, 0x3d800000, v103
	v_fmamk_f32 v0, v0, 0x3d800000, v102
	ds_bpermute_b32 v146, v192, v0
	ds_bpermute_b32 v147, v193, v0
	ds_bpermute_b32 v145, v191, v0
	s_waitcnt lgkmcnt(2)
	v_cndmask_b32_e64 v146, 0, v146, s[28:29]
	s_waitcnt lgkmcnt(1)
	v_cndmask_b32_e64 v147, v147, 0, s[8:9]
	v_add_f32_e32 v146, v146, v147
	s_waitcnt lgkmcnt(0)
	v_cndmask_b32_e64 v145, 0, v145, s[4:5]
	v_add_f32_e32 v145, v145, v146
	v_add_f32_e32 v0, v145, v0
	v_add_f32_e32 v102, v145, v102
	ds_write2st64_b32 v204, v0, v102 offset0:24 offset1:26
	v_add_f32_e32 v0, v145, v103
	v_add_f32_e32 v102, v145, v104
	ds_write2st64_b32 v204, v0, v102 offset0:28 offset1:30
	v_add_f32_e32 v0, v145, v106
	v_add_f32_e32 v102, v145, v107
	ds_write2st64_b32 v204, v0, v102 offset0:32 offset1:34
	v_add_f32_e32 v0, v145, v108
	v_add_f32_e32 v102, v145, v109
	ds_write2st64_b32 v204, v0, v102 offset0:36 offset1:38
	v_add_f32_e32 v0, v145, v137
	v_add_f32_e32 v102, v145, v144
	ds_write2st64_b32 v204, v0, v102 offset0:40 offset1:42
	v_add_f32_e32 v0, v145, v143
	v_add_f32_e32 v102, v145, v142
	ds_write2st64_b32 v204, v0, v102 offset0:44 offset1:46
	v_add_f32_e32 v0, v145, v135
	v_add_f32_e32 v102, v145, v140
	ds_write2st64_b32 v204, v0, v102 offset0:48 offset1:50
	v_add_f32_e32 v0, v145, v141
	v_add_f32_e32 v102, v145, v105
	ds_write2st64_b32 v204, v0, v102 offset0:52 offset1:54
	s_waitcnt lgkmcnt(0)
	s_barrier
	s_and_saveexec_b64 s[62:63], s[10:11]
	s_cbranch_execz .LBB0_2285
	ds_read_b32 v0, v181 offset:6144
	v_lshl_add_u32 v102, s68, 9, v181
	s_waitcnt lgkmcnt(0)
	ds_write_b32 v102, v0 offset:4096
